# GU GEMM loop: LDS-DMA loads in scalar-base form, no 64-bit VALU address adds in the load segments
# speedup vs baseline: 1.0089x; 1.0089x over previous
;     __device__ __forceinline__ void stage_rs(const Unit& u, int tid, int wid) const { stage_rs_lds(SS, rsl, u, tid, wid); }
;     __device__ __forceinline__ void stage_rs(const Unit& u, int tid, int wid) const { stage_rs_lds(SS, rsl, u, tid, wid); }
; #define PG8_STAGE(bufoff, gbase, voff) do { _Pragma("unroll") for (int _i = 0; _i < 2; ++_i) \
;         __builtin_amdgcn_global_load_lds((const unsigned*)((const char*)(gbase) + (voff)[_i]), (PG8_LAS unsigned*)(lds + (bufoff) + ldsw + _i * 8192), 16, 0, 0); } while (0)
; #define PG8_LDA(dst, b, h) do { _Pragma("unroll") for (int m = 0; m < 4; ++m) _Pragma("unroll") for (int k = 0; k < 2; ++k) dst[m][k] = *(const PG8_LAS bf16x8*)(lds + PG8_SA(b, h) + aoff + m * 2048 + k * 1024); } while (0)
; #define PG8_LDB(dst, b, h) do { _Pragma("unroll") for (int n = 0; n < 2; ++n) _Pragma("unroll") for (int k = 0; k < 2; ++k) dst[n][k] = *(const PG8_LAS bf16x8*)(lds + PG8_SB(b, h) + boff + n * 2048 + k * 1024); } while (0)
; #define PG8_BAR __builtin_amdgcn_s_barrier()
; template <class Epi, class Sched, bool ALIGN_EPI = false, bool SP2 = false>
; __device__ __forceinline__ void gemm_phase(PG8_LAS unsigned char* lds, const Gemm g, const Sched& S, const Epi& E, const int tid) {
;     ...
;         for (int t = 0; t < nt; t += 2) {
;             const bool last = (t == nt - 2);
;             if constexpr (Epi::RS_LDS) { if (t == nt - 4) E.stage_rs(cur, tid, wid); }
;             if constexpr (Epi::PREFETCH) { if (t >= nt - 8) E.prefetch(cur, lds, tid, wid, (t - (nt - 8)) >> 1); }
;             const char* a1 = cA + (size_t)(t + 1) * kstep;
;             const char* a2 = last ? nA : cA + (size_t)(t + 2) * kstep; const char* b2 = last ? nB : cB + (size_t)(t + 2) * kstep;
;             const char* a3 = a2 + kstep; const char* b3 = b2 + kstep;
;             if (last && has_next) S.a_ready(nxt);
;             if constexpr (SP2) {
;             PG8_LDB(B0, 0, 0); PG8_LDB(B1, 0, 1); PG8_SCHED; PG8_LDA(At, 0, 0); PG8_STAGE(PG8_SA(1, 1), a1 + hstep, voffA);
;             PG8_WAIT_V(8); PG8_WAIT_L(0); PG8_BAR; PG8_MMA(0, 0, At, B0); PG8_MMA(0, 1, At, B1); PG8_BAR; PG8_SCHED;
;             PG8_LDA(At, 0, 1); PG8_STAGE(PG8_SB(0, 0), b2, voffB); PG8_STAGE(PG8_SB(0, 1), b2 + hstep, voffB); PG8_STAGE(PG8_SA(0, 0), a2, voffA);
;             PG8_WAIT_V(8); PG8_WAIT_L(0); PG8_BAR; PG8_MMA(1, 0, At, B0); PG8_MMA(1, 1, At, B1); PG8_BAR; PG8_SCHED;
.LBB0_87:
	s_add_u32 s38, s22, s68
	s_addc_u32 s39, s23, s69
	s_add_u32 s38, s38, 0x100
	s_addc_u32 s39, s39, 0
	s_add_u32 s94, s38, 0x3ff80
	s_addc_u32 s95, s39, 0
	s_add_u32 s50, s89, s68
	s_addc_u32 s51, s90, s69
	s_add_i32 s92, 0, 0x10000
	s_cmpk_eq_i32 s68, 0x700
	s_cselect_b32 s73, s15, s39
	s_cselect_b32 s72, s86, s38
	v_add_u32_e32 v150, s92, v153
	s_cselect_b32 s71, s87, s51
	s_cselect_b32 s70, s88, s50
	s_add_i32 s38, 0, 0x14000
	ds_read_b128 v[170:173], v150
	ds_read_b128 v[174:177], v150 offset:1024
	ds_read_b128 v[178:181], v150 offset:2048
	ds_read_b128 v[182:185], v150 offset:3072
	v_add_u32_e32 v150, s38, v153
	ds_read_b128 v[186:189], v150
	ds_read_b128 v[190:193], v150 offset:1024
	ds_read_b128 v[206:209], v150 offset:2048
	ds_read_b128 v[210:213], v150 offset:3072
	s_add_i32 m0, s76, 0xc000
	ds_read_b128 v[214:217], v167
	ds_read_b128 v[218:221], v167 offset:1024
	ds_read_b128 v[222:225], v167 offset:2048
	ds_read_b128 v[226:229], v167 offset:3072
	ds_read_b128 v[230:233], v167 offset:4096
	ds_read_b128 v[234:237], v167 offset:5120
	ds_read_b128 v[238:241], v167 offset:6144
	ds_read_b128 v[242:245], v167 offset:7168
	global_load_lds_dwordx4 v138, s[94:95]
	s_add_i32 m0, s76, 0xe000
	s_nop 0
	global_load_lds_dwordx4 v140, s[94:95]
	s_waitcnt vmcnt(8)
	s_waitcnt lgkmcnt(0)
	s_setprio 1
	s_barrier
	v_mfma_f32_16x16x32_bf16 v[126:129], v[170:173], v[214:217], v[126:129]
	v_mfma_f32_16x16x32_bf16 v[122:125], v[178:181], v[214:217], v[122:125]
	v_mfma_f32_16x16x32_bf16 v[110:113], v[170:173], v[222:225], v[110:113]
	v_mfma_f32_16x16x32_bf16 v[106:109], v[178:181], v[222:225], v[106:109]
	v_mfma_f32_16x16x32_bf16 v[94:97], v[170:173], v[230:233], v[94:97]
	v_mfma_f32_16x16x32_bf16 v[90:93], v[178:181], v[230:233], v[90:93]
	v_mfma_f32_16x16x32_bf16 v[78:81], v[170:173], v[238:241], v[78:81]
	v_mfma_f32_16x16x32_bf16 v[74:77], v[178:181], v[238:241], v[74:77]
	v_mfma_f32_16x16x32_bf16 v[126:129], v[174:177], v[218:221], v[126:129]
	v_mfma_f32_16x16x32_bf16 v[122:125], v[182:185], v[218:221], v[122:125]
	v_mfma_f32_16x16x32_bf16 v[110:113], v[174:177], v[226:229], v[110:113]
	v_mfma_f32_16x16x32_bf16 v[106:109], v[182:185], v[226:229], v[106:109]
	v_mfma_f32_16x16x32_bf16 v[94:97], v[174:177], v[234:237], v[94:97]
	v_mfma_f32_16x16x32_bf16 v[90:93], v[182:185], v[234:237], v[90:93]
	v_mfma_f32_16x16x32_bf16 v[78:81], v[174:177], v[242:245], v[78:81]
	v_mfma_f32_16x16x32_bf16 v[74:77], v[182:185], v[242:245], v[74:77]
	v_mfma_f32_16x16x32_bf16 v[118:121], v[186:189], v[214:217], v[118:121]
	v_mfma_f32_16x16x32_bf16 v[114:117], v[206:209], v[214:217], v[114:117]
	v_mfma_f32_16x16x32_bf16 v[102:105], v[186:189], v[222:225], v[102:105]
	v_mfma_f32_16x16x32_bf16 v[98:101], v[206:209], v[222:225], v[98:101]
	v_mfma_f32_16x16x32_bf16 v[86:89], v[186:189], v[230:233], v[86:89]
	v_mfma_f32_16x16x32_bf16 v[82:85], v[206:209], v[230:233], v[82:85]
	v_mfma_f32_16x16x32_bf16 v[70:73], v[186:189], v[238:241], v[70:73]
	v_mfma_f32_16x16x32_bf16 v[66:69], v[206:209], v[238:241], v[66:69]
	v_mfma_f32_16x16x32_bf16 v[118:121], v[190:193], v[218:221], v[118:121]
	v_mfma_f32_16x16x32_bf16 v[114:117], v[210:213], v[218:221], v[114:117]
	v_mfma_f32_16x16x32_bf16 v[102:105], v[190:193], v[226:229], v[102:105]
	v_mfma_f32_16x16x32_bf16 v[98:101], v[210:213], v[226:229], v[98:101]
	v_mfma_f32_16x16x32_bf16 v[86:89], v[190:193], v[234:237], v[86:89]
	v_mfma_f32_16x16x32_bf16 v[82:85], v[210:213], v[234:237], v[82:85]
	v_mfma_f32_16x16x32_bf16 v[70:73], v[190:193], v[242:245], v[70:73]
	v_mfma_f32_16x16x32_bf16 v[66:69], v[210:213], v[242:245], v[66:69]
	s_setprio 0
	s_barrier
	s_add_i32 s39, s92, s75
	s_mov_b32 m0, s39
	ds_read_b128 v[214:217], v167 offset:16384
	ds_read_b128 v[218:221], v167 offset:17408
	ds_read_b128 v[222:225], v167 offset:18432
	ds_read_b128 v[226:229], v167 offset:19456
	ds_read_b128 v[230:233], v167 offset:20480
	ds_read_b128 v[234:237], v167 offset:21504
	ds_read_b128 v[238:241], v167 offset:22528
	ds_read_b128 v[242:245], v167 offset:23552
	global_load_lds_dwordx4 v0, s[70:71]
	s_add_i32 m0, s39, 0x2000
	s_add_u32 s50, s70, 0x40000
	s_addc_u32 s51, s71, 0
	s_add_i32 s38, s38, s75
	global_load_lds_dwordx4 v130, s[70:71]
	s_mov_b32 m0, s38
	s_nop 0
	global_load_lds_dwordx4 v0, s[50:51]
	s_add_i32 m0, s38, 0x2000
	s_nop 0
	global_load_lds_dwordx4 v130, s[50:51]
	s_mov_b32 m0, s76
	s_nop 0
	global_load_lds_dwordx4 v134, s[72:73]
	s_mov_b32 m0, s77
	s_nop 0
	global_load_lds_dwordx4 v132, s[72:73]
	s_waitcnt vmcnt(8)
	s_waitcnt lgkmcnt(0)
	s_setprio 1
	s_barrier
; #define PG8_STAGE(bufoff, gbase, voff) do { _Pragma("unroll") for (int _i = 0; _i < 2; ++_i) \
;         __builtin_amdgcn_global_load_lds((const unsigned*)((const char*)(gbase) + (voff)[_i]), (PG8_LAS unsigned*)(lds + (bufoff) + ldsw + _i * 8192), 16, 0, 0); } while (0)
; #define PG8_LDA(dst, b, h) do { _Pragma("unroll") for (int m = 0; m < 4; ++m) _Pragma("unroll") for (int k = 0; k < 2; ++k) dst[m][k] = *(const PG8_LAS bf16x8*)(lds + PG8_SA(b, h) + aoff + m * 2048 + k * 1024); } while (0)
; #define PG8_LDB(dst, b, h) do { _Pragma("unroll") for (int n = 0; n < 2; ++n) _Pragma("unroll") for (int k = 0; k < 2; ++k) dst[n][k] = *(const PG8_LAS bf16x8*)(lds + PG8_SB(b, h) + boff + n * 2048 + k * 1024); } while (0)
; #define PG8_MMA(ai, bj, At, Bt) do { __builtin_amdgcn_s_setprio(1); _Pragma("unroll") for (int m = 0; m < 4; ++m) _Pragma("unroll") for (int n = 0; n < 2; ++n) _Pragma("unroll") for (int k = 0; k < 2; ++k) \
;         acc[ai][bj][m][n] = __builtin_amdgcn_mfma_f32_16x16x32_bf16(Bt[n][k], At[m][k], acc[ai][bj][m][n], 0, 0, 0); __builtin_amdgcn_s_setprio(0); } while (0)
; #define PG8_WAIT_V(n) asm volatile("s_waitcnt vmcnt(" #n ")" ::: "memory")
; #define PG8_WAIT_L(n) asm volatile("s_waitcnt lgkmcnt(" #n ")" ::: "memory")
; #define PG8_BAR __builtin_amdgcn_s_barrier()
; #define PG8_SCHED __builtin_amdgcn_sched_barrier(0)
; template <class Epi, class Sched, bool ALIGN_EPI = false, bool SP2 = false>
; __device__ __forceinline__ void gemm_phase(PG8_LAS unsigned char* lds, const Gemm g, const Sched& S, const Epi& E, const int tid) {
;     ...
;             PG8_WAIT_V(8); PG8_WAIT_L(0); PG8_BAR; PG8_MMA(1, 0, At, B0); PG8_MMA(1, 1, At, B1); PG8_BAR; PG8_SCHED;
;             PG8_LDB(B0, 1, 0); PG8_LDB(B1, 1, 1); PG8_SCHED; PG8_LDA(At, 1, 0); PG8_STAGE(PG8_SA(0, 1), a2 + hstep, voffA);
;             PG8_WAIT_V(8); PG8_WAIT_L(0); PG8_BAR; PG8_MMA(0, 0, At, B0); PG8_MMA(0, 1, At, B1); PG8_BAR; PG8_SCHED;
	v_mfma_f32_16x16x32_bf16 v[62:65], v[170:173], v[214:217], v[62:65]
	v_mfma_f32_16x16x32_bf16 v[58:61], v[178:181], v[214:217], v[58:61]
	v_mfma_f32_16x16x32_bf16 v[46:49], v[170:173], v[222:225], v[46:49]
	v_mfma_f32_16x16x32_bf16 v[42:45], v[178:181], v[222:225], v[42:45]
	v_mfma_f32_16x16x32_bf16 v[30:33], v[170:173], v[230:233], v[30:33]
	v_mfma_f32_16x16x32_bf16 v[26:29], v[178:181], v[230:233], v[26:29]
	v_mfma_f32_16x16x32_bf16 v[14:17], v[170:173], v[238:241], v[14:17]
	v_mfma_f32_16x16x32_bf16 v[10:13], v[178:181], v[238:241], v[10:13]
	v_mfma_f32_16x16x32_bf16 v[62:65], v[174:177], v[218:221], v[62:65]
	v_mfma_f32_16x16x32_bf16 v[58:61], v[182:185], v[218:221], v[58:61]
	v_mfma_f32_16x16x32_bf16 v[46:49], v[174:177], v[226:229], v[46:49]
	v_mfma_f32_16x16x32_bf16 v[42:45], v[182:185], v[226:229], v[42:45]
	v_mfma_f32_16x16x32_bf16 v[30:33], v[174:177], v[234:237], v[30:33]
	v_mfma_f32_16x16x32_bf16 v[26:29], v[182:185], v[234:237], v[26:29]
	v_mfma_f32_16x16x32_bf16 v[14:17], v[174:177], v[242:245], v[14:17]
	v_mfma_f32_16x16x32_bf16 v[10:13], v[182:185], v[242:245], v[10:13]
	v_mfma_f32_16x16x32_bf16 v[54:57], v[186:189], v[214:217], v[54:57]
	v_mfma_f32_16x16x32_bf16 v[50:53], v[206:209], v[214:217], v[50:53]
	v_mfma_f32_16x16x32_bf16 v[38:41], v[186:189], v[222:225], v[38:41]
	v_mfma_f32_16x16x32_bf16 v[34:37], v[206:209], v[222:225], v[34:37]
	v_mfma_f32_16x16x32_bf16 v[22:25], v[186:189], v[230:233], v[22:25]
	v_mfma_f32_16x16x32_bf16 v[18:21], v[206:209], v[230:233], v[18:21]
	v_mfma_f32_16x16x32_bf16 v[6:9], v[186:189], v[238:241], v[6:9]
	v_mfma_f32_16x16x32_bf16 v[2:5], v[206:209], v[238:241], v[2:5]
	v_mfma_f32_16x16x32_bf16 v[54:57], v[190:193], v[218:221], v[54:57]
	v_mfma_f32_16x16x32_bf16 v[50:53], v[210:213], v[218:221], v[50:53]
	v_mfma_f32_16x16x32_bf16 v[38:41], v[190:193], v[226:229], v[38:41]
	v_mfma_f32_16x16x32_bf16 v[34:37], v[210:213], v[226:229], v[34:37]
	v_mfma_f32_16x16x32_bf16 v[22:25], v[190:193], v[234:237], v[22:25]
	v_mfma_f32_16x16x32_bf16 v[18:21], v[210:213], v[234:237], v[18:21]
	v_mfma_f32_16x16x32_bf16 v[6:9], v[190:193], v[242:245], v[6:9]
	v_mfma_f32_16x16x32_bf16 v[2:5], v[210:213], v[242:245], v[2:5]
	s_setprio 0
	s_barrier
	s_add_i32 s38, 0, 0x18000
	v_add_u32_e32 v150, s38, v153
	s_add_i32 s39, 0, 0x1c000
	ds_read_b128 v[170:173], v150
	ds_read_b128 v[174:177], v150 offset:1024
	ds_read_b128 v[178:181], v150 offset:2048
	ds_read_b128 v[182:185], v150 offset:3072
	v_add_u32_e32 v150, s39, v153
	ds_read_b128 v[186:189], v150
	ds_read_b128 v[190:193], v150 offset:1024
	ds_read_b128 v[206:209], v150 offset:2048
	ds_read_b128 v[210:213], v150 offset:3072
	s_add_u32 s50, s72, 0x40000
	s_addc_u32 s51, s73, 0
	s_mov_b32 m0, s78
	ds_read_b128 v[214:217], v167 offset:32768
	ds_read_b128 v[218:221], v167 offset:33792
	ds_read_b128 v[222:225], v167 offset:34816
	ds_read_b128 v[226:229], v167 offset:35840
	ds_read_b128 v[230:233], v167 offset:36864
	ds_read_b128 v[234:237], v167 offset:37888
	ds_read_b128 v[238:241], v167 offset:38912
	ds_read_b128 v[242:245], v167 offset:39936
	global_load_lds_dwordx4 v134, s[50:51]
	s_mov_b32 m0, s79
	s_nop 0
	global_load_lds_dwordx4 v132, s[50:51]
	s_waitcnt vmcnt(8)
	s_waitcnt lgkmcnt(0)
	s_setprio 1
	s_barrier
	v_mfma_f32_16x16x32_bf16 v[126:129], v[170:173], v[214:217], v[126:129]
	v_mfma_f32_16x16x32_bf16 v[122:125], v[178:181], v[214:217], v[122:125]
	v_mfma_f32_16x16x32_bf16 v[110:113], v[170:173], v[222:225], v[110:113]
	v_mfma_f32_16x16x32_bf16 v[106:109], v[178:181], v[222:225], v[106:109]
	v_mfma_f32_16x16x32_bf16 v[94:97], v[170:173], v[230:233], v[94:97]
	v_mfma_f32_16x16x32_bf16 v[90:93], v[178:181], v[230:233], v[90:93]
	v_mfma_f32_16x16x32_bf16 v[78:81], v[170:173], v[238:241], v[78:81]
	v_mfma_f32_16x16x32_bf16 v[74:77], v[178:181], v[238:241], v[74:77]
	v_mfma_f32_16x16x32_bf16 v[126:129], v[174:177], v[218:221], v[126:129]
	v_mfma_f32_16x16x32_bf16 v[122:125], v[182:185], v[218:221], v[122:125]
	v_mfma_f32_16x16x32_bf16 v[110:113], v[174:177], v[226:229], v[110:113]
	v_mfma_f32_16x16x32_bf16 v[106:109], v[182:185], v[226:229], v[106:109]
	v_mfma_f32_16x16x32_bf16 v[94:97], v[174:177], v[234:237], v[94:97]
	v_mfma_f32_16x16x32_bf16 v[90:93], v[182:185], v[234:237], v[90:93]
	v_mfma_f32_16x16x32_bf16 v[78:81], v[174:177], v[242:245], v[78:81]
	v_mfma_f32_16x16x32_bf16 v[74:77], v[182:185], v[242:245], v[74:77]
	v_mfma_f32_16x16x32_bf16 v[118:121], v[186:189], v[214:217], v[118:121]
	v_mfma_f32_16x16x32_bf16 v[114:117], v[206:209], v[214:217], v[114:117]
	v_mfma_f32_16x16x32_bf16 v[102:105], v[186:189], v[222:225], v[102:105]
	v_mfma_f32_16x16x32_bf16 v[98:101], v[206:209], v[222:225], v[98:101]
	v_mfma_f32_16x16x32_bf16 v[86:89], v[186:189], v[230:233], v[86:89]
	v_mfma_f32_16x16x32_bf16 v[82:85], v[206:209], v[230:233], v[82:85]
	v_mfma_f32_16x16x32_bf16 v[70:73], v[186:189], v[238:241], v[70:73]
	v_mfma_f32_16x16x32_bf16 v[66:69], v[206:209], v[238:241], v[66:69]
	v_mfma_f32_16x16x32_bf16 v[118:121], v[190:193], v[218:221], v[118:121]
	v_mfma_f32_16x16x32_bf16 v[114:117], v[210:213], v[218:221], v[114:117]
	v_mfma_f32_16x16x32_bf16 v[102:105], v[190:193], v[226:229], v[102:105]
	v_mfma_f32_16x16x32_bf16 v[98:101], v[210:213], v[226:229], v[98:101]
	v_mfma_f32_16x16x32_bf16 v[86:89], v[190:193], v[234:237], v[86:89]
	v_mfma_f32_16x16x32_bf16 v[82:85], v[210:213], v[234:237], v[82:85]
	v_mfma_f32_16x16x32_bf16 v[70:73], v[190:193], v[242:245], v[70:73]
	v_mfma_f32_16x16x32_bf16 v[66:69], v[210:213], v[242:245], v[66:69]
	s_setprio 0
	s_barrier
; #define PG8_STAGE(bufoff, gbase, voff) do { _Pragma("unroll") for (int _i = 0; _i < 2; ++_i) \
;         __builtin_amdgcn_global_load_lds((const unsigned*)((const char*)(gbase) + (voff)[_i]), (PG8_LAS unsigned*)(lds + (bufoff) + ldsw + _i * 8192), 16, 0, 0); } while (0)
; #define PG8_LDA(dst, b, h) do { _Pragma("unroll") for (int m = 0; m < 4; ++m) _Pragma("unroll") for (int k = 0; k < 2; ++k) dst[m][k] = *(const PG8_LAS bf16x8*)(lds + PG8_SA(b, h) + aoff + m * 2048 + k * 1024); } while (0)
; #define PG8_MMA(ai, bj, At, Bt) do { __builtin_amdgcn_s_setprio(1); _Pragma("unroll") for (int m = 0; m < 4; ++m) _Pragma("unroll") for (int n = 0; n < 2; ++n) _Pragma("unroll") for (int k = 0; k < 2; ++k) \
;         acc[ai][bj][m][n] = __builtin_amdgcn_mfma_f32_16x16x32_bf16(Bt[n][k], At[m][k], acc[ai][bj][m][n], 0, 0, 0); __builtin_amdgcn_s_setprio(0); } while (0)
; #define PG8_WAIT_V(n) asm volatile("s_waitcnt vmcnt(" #n ")" ::: "memory")
; #define PG8_WAIT_L(n) asm volatile("s_waitcnt lgkmcnt(" #n ")" ::: "memory")
; #define PG8_BAR __builtin_amdgcn_s_barrier()
; #define PG8_SCHED __builtin_amdgcn_sched_barrier(0)
; template <class Epi, class Sched, bool ALIGN_EPI = false, bool SP2 = false>
; __device__ __forceinline__ void gemm_phase(PG8_LAS unsigned char* lds, const Gemm g, const Sched& S, const Epi& E, const int tid) {
;     ...
;             PG8_LDA(At, 1, 1); PG8_STAGE(PG8_SB(1, 0), b3, voffB); PG8_STAGE(PG8_SB(1, 1), b3 + hstep, voffB); PG8_STAGE(PG8_SA(1, 0), a3, voffA);
;             PG8_WAIT_V(8); PG8_WAIT_L(0); PG8_BAR; PG8_MMA(1, 0, At, B0); PG8_MMA(1, 1, At, B1); PG8_BAR; PG8_SCHED;
	s_add_i32 s38, s38, s75
	s_add_u32 s94, s70, 0x80
	s_addc_u32 s95, s71, 0
	s_mov_b32 m0, s38
	ds_read_b128 v[214:217], v167 offset:49152
	ds_read_b128 v[218:221], v167 offset:50176
	ds_read_b128 v[222:225], v167 offset:51200
	ds_read_b128 v[226:229], v167 offset:52224
	ds_read_b128 v[230:233], v167 offset:53248
	ds_read_b128 v[234:237], v167 offset:54272
	ds_read_b128 v[238:241], v167 offset:55296
	ds_read_b128 v[242:245], v167 offset:56320
	global_load_lds_dwordx4 v0, s[94:95]
	s_add_i32 m0, s38, 0x2000
	s_add_u32 s50, s70, 0x40080
	s_addc_u32 s51, s71, 0
	s_add_i32 s38, s39, s75
	global_load_lds_dwordx4 v130, s[94:95]
	s_mov_b32 m0, s38
	s_nop 0
	global_load_lds_dwordx4 v0, s[50:51]
	s_add_i32 m0, s38, 0x2000
	s_nop 0
	global_load_lds_dwordx4 v130, s[50:51]
	s_add_u32 s94, s72, 0x80
	s_addc_u32 s95, s73, 0
	s_mov_b32 m0, s80
	s_nop 0
	global_load_lds_dwordx4 v134, s[94:95]
	s_mov_b32 m0, s81
	s_nop 0
	global_load_lds_dwordx4 v132, s[94:95]
	s_waitcnt vmcnt(8)
	s_waitcnt lgkmcnt(0)
	s_setprio 1
	s_barrier
	v_mfma_f32_16x16x32_bf16 v[62:65], v[170:173], v[214:217], v[62:65]
	v_mfma_f32_16x16x32_bf16 v[58:61], v[178:181], v[214:217], v[58:61]
	v_mfma_f32_16x16x32_bf16 v[46:49], v[170:173], v[222:225], v[46:49]
	v_mfma_f32_16x16x32_bf16 v[42:45], v[178:181], v[222:225], v[42:45]
	v_mfma_f32_16x16x32_bf16 v[30:33], v[170:173], v[230:233], v[30:33]
	v_mfma_f32_16x16x32_bf16 v[26:29], v[178:181], v[230:233], v[26:29]
	v_mfma_f32_16x16x32_bf16 v[14:17], v[170:173], v[238:241], v[14:17]
	v_mfma_f32_16x16x32_bf16 v[10:13], v[178:181], v[238:241], v[10:13]
	v_mfma_f32_16x16x32_bf16 v[62:65], v[174:177], v[218:221], v[62:65]
	v_mfma_f32_16x16x32_bf16 v[58:61], v[182:185], v[218:221], v[58:61]
	v_mfma_f32_16x16x32_bf16 v[46:49], v[174:177], v[226:229], v[46:49]
	v_mfma_f32_16x16x32_bf16 v[42:45], v[182:185], v[226:229], v[42:45]
	v_mfma_f32_16x16x32_bf16 v[30:33], v[174:177], v[234:237], v[30:33]
	v_mfma_f32_16x16x32_bf16 v[26:29], v[182:185], v[234:237], v[26:29]
	v_mfma_f32_16x16x32_bf16 v[14:17], v[174:177], v[242:245], v[14:17]
	v_mfma_f32_16x16x32_bf16 v[10:13], v[182:185], v[242:245], v[10:13]
	v_mfma_f32_16x16x32_bf16 v[54:57], v[186:189], v[214:217], v[54:57]
	v_mfma_f32_16x16x32_bf16 v[50:53], v[206:209], v[214:217], v[50:53]
	v_mfma_f32_16x16x32_bf16 v[38:41], v[186:189], v[222:225], v[38:41]
	v_mfma_f32_16x16x32_bf16 v[34:37], v[206:209], v[222:225], v[34:37]
	v_mfma_f32_16x16x32_bf16 v[22:25], v[186:189], v[230:233], v[22:25]
	v_mfma_f32_16x16x32_bf16 v[18:21], v[206:209], v[230:233], v[18:21]
	v_mfma_f32_16x16x32_bf16 v[6:9], v[186:189], v[238:241], v[6:9]
	v_mfma_f32_16x16x32_bf16 v[2:5], v[206:209], v[238:241], v[2:5]
	v_mfma_f32_16x16x32_bf16 v[54:57], v[190:193], v[218:221], v[54:57]
	v_mfma_f32_16x16x32_bf16 v[50:53], v[210:213], v[218:221], v[50:53]
	v_mfma_f32_16x16x32_bf16 v[38:41], v[190:193], v[226:229], v[38:41]
	v_mfma_f32_16x16x32_bf16 v[34:37], v[210:213], v[226:229], v[34:37]
	v_mfma_f32_16x16x32_bf16 v[22:25], v[190:193], v[234:237], v[22:25]
	v_mfma_f32_16x16x32_bf16 v[18:21], v[210:213], v[234:237], v[18:21]
	v_mfma_f32_16x16x32_bf16 v[6:9], v[190:193], v[242:245], v[6:9]
	v_mfma_f32_16x16x32_bf16 v[2:5], v[210:213], v[242:245], v[2:5]
	s_setprio 0
	s_barrier
	s_add_i32 s91, s91, 2
	s_add_u32 s68, s68, 0x100
	s_addc_u32 s69, s69, 0
	s_cmp_gt_u32 s91, 13
	s_cbranch_scc1 .LBB0_90
